# v16 + stick-breaking tile loop: K/V tile loads stay in flight across steps (loads every step, vmcnt(4) at the LDS stores, q fragments waited once, drain at loop exit)
# speedup vs baseline: 1.0056x; 1.0033x over previous
; #define LOADT(i, kreg, vreg, creg) do { const int k0_ = KEY0(i); kreg = *(const u32x4*)(A.K + (size_t)(k0_ + lane) * A.ldkv + wid * 8); vreg = *(const u32x4*)(A.V + (size_t)(k0_ + lane) * A.ldkv + wid * 8); \
;         if (MODE == M_FOX) { if (tid < 64) creg = A.cf[k0_ + tid] * LOG2E; } } while (0)
; template <int MODE>
; __device__ __forceinline__ void attn_unit(LAS unsigned char* lds, const AttnArgs& A, int qb) {
;     ...
;     for (int i0 = 0; i0 < NT; i0 += 3) {
;         { const int i = i0 + 0; if (i >= NT) break;
;         const int key0 = KEY0(i);
;         if (i + 3 < NT) LOADT(i + 3, k1, v1, c1);
.LBB0_1166:
	s_add_i32 s80, s0, 3
	s_cmp_lt_u32 s80, s2
	s_cselect_b64 s[96:97], -1, 0
	s_cmp_ge_u32 s80, s2
	v_add_u32_e32 v2, s1, v130
	v_add_u32_e32 v2, 0xffffff01, v2
	v_ashrrev_i32_e32 v3, 31, v2
	v_lshlrev_b64 v[2:3], 11, v[2:3]
	v_lshl_add_u64 v[4:5], s[88:89], 0, v[2:3]
	v_lshl_add_u64 v[2:3], s[90:91], 0, v[2:3]
	global_load_dwordx4 v[66:69], v[2:3], off
	global_load_dwordx4 v[70:73], v[4:5], off

; template <int MODE>
; __device__ __forceinline__ void attn_unit(LAS unsigned char* lds, const AttnArgs& A, int qb) {
;     ...
;         if (i + 1 < NT) STORET(1, k2, v2, c2);
.LBB0_1176:
	s_add_i32 s10, s0, 1
	s_cmp_lt_u32 s10, s2
	s_cselect_b64 s[12:13], -1, 0
	s_cmp_ge_u32 s10, s2
	s_cbranch_scc1 .LBB0_1178
	v_add_u32_e32 v34, s84, v123
	s_waitcnt vmcnt(4)
	ds_write_b128 v34, v[90:93] offset:17664
	v_add_u32_e32 v34, s79, v131
	s_waitcnt vmcnt(4)
	ds_write_b16 v34, v94 offset:25856
	ds_write_b16_d16_hi v34, v94 offset:26000
	ds_write_b16 v34, v95 offset:26144
	ds_write_b16_d16_hi v34, v95 offset:26288
	ds_write_b16 v34, v96 offset:26432
	ds_write_b16_d16_hi v34, v96 offset:26576
	ds_write_b16 v34, v97 offset:26720
	ds_write_b16_d16_hi v34, v97 offset:26864

; #define LOADT(i, kreg, vreg, creg) do { const int k0_ = KEY0(i); kreg = *(const u32x4*)(A.K + (size_t)(k0_ + lane) * A.ldkv + wid * 8); vreg = *(const u32x4*)(A.V + (size_t)(k0_ + lane) * A.ldkv + wid * 8); \
;         if (MODE == M_FOX) { if (tid < 64) creg = A.cf[k0_ + tid] * LOG2E; } } while (0)
; template <int MODE>
; __device__ __forceinline__ void attn_unit(LAS unsigned char* lds, const AttnArgs& A, int qb) {
;     ...
;         if (i + 3 < NT) LOADT(i + 3, k2, v2, c2);
.LBB0_1182:
	s_andn2_b64 vcc, exec, s[12:13]
	s_cbranch_vccnz .LBB0_1193
	s_cmp_ge_u32 s0, s76
	v_add_u32_e32 v34, s1, v130
	v_add_u32_e32 v34, 0xfffffec1, v34
	v_ashrrev_i32_e32 v35, 31, v34
	v_lshlrev_b64 v[34:35], 11, v[34:35]
	v_lshl_add_u64 v[36:37], s[88:89], 0, v[34:35]
	v_lshl_add_u64 v[34:35], s[90:91], 0, v[34:35]
	global_load_dwordx4 v[90:93], v[34:35], off
	global_load_dwordx4 v[94:97], v[36:37], off

; template <int MODE>
; __device__ __forceinline__ void attn_unit(LAS unsigned char* lds, const AttnArgs& A, int qb) {
;     ...
;         if (i + 1 < NT) STORET(2, k3, v3, c3);
.LBB0_1196:
	v_add_u32_e32 v34, s84, v123
	s_waitcnt vmcnt(4)
	ds_write_b128 v34, v[98:101] offset:35328
	v_add_u32_e32 v34, s79, v131
	s_waitcnt vmcnt(4)
	ds_write_b16 v34, v102 offset:43520
	ds_write_b16_d16_hi v34, v102 offset:43664
	ds_write_b16 v34, v103 offset:43808
	ds_write_b16_d16_hi v34, v103 offset:43952
	ds_write_b16 v34, v104 offset:44096
	ds_write_b16_d16_hi v34, v104 offset:44240
	ds_write_b16 v34, v105 offset:44384
	ds_write_b16_d16_hi v34, v105 offset:44528

; #define LOADT(i, kreg, vreg, creg) do { const int k0_ = KEY0(i); kreg = *(const u32x4*)(A.K + (size_t)(k0_ + lane) * A.ldkv + wid * 8); vreg = *(const u32x4*)(A.V + (size_t)(k0_ + lane) * A.ldkv + wid * 8); \
;         if (MODE == M_FOX) { if (tid < 64) creg = A.cf[k0_ + tid] * LOG2E; } } while (0)
; template <int MODE>
; __device__ __forceinline__ void attn_unit(LAS unsigned char* lds, const AttnArgs& A, int qb) {
;     ...
;         { const int i = i0 + 2; if (i >= NT) break;
;         const int key0 = KEY0(i);
;         if (i + 3 < NT) LOADT(i + 3, k3, v3, c3);
.LBB0_1200:
	s_add_i32 s10, s0, 2
	s_cmp_ge_u32 s10, s2
	s_mov_b64 s[10:11], 0
	s_cbranch_scc1 .LBB0_1211
	s_add_i32 s0, s0, 5
	s_cmp_ge_u32 s0, s2
	v_add_u32_e32 v34, s1, v130
	v_add_u32_e32 v34, 0xfffffe81, v34
	v_ashrrev_i32_e32 v35, 31, v34
	v_lshlrev_b64 v[34:35], 11, v[34:35]
	v_lshl_add_u64 v[36:37], s[88:89], 0, v[34:35]
	v_lshl_add_u64 v[34:35], s[90:91], 0, v[34:35]
	global_load_dwordx4 v[98:101], v[34:35], off
	global_load_dwordx4 v[102:105], v[36:37], off

; template <int MODE>
; __device__ __forceinline__ void attn_unit(LAS unsigned char* lds, const AttnArgs& A, int qb) {
;     ...
;         if (i + 1 < NT) STORET(0, k1, v1, c1);
.LBB0_1213:
	s_waitcnt vmcnt(4)
	ds_write_b128 v133, v[66:69]
	s_waitcnt vmcnt(4)
	ds_write_b16 v134, v70 offset:8192
	ds_write_b16_d16_hi v134, v70 offset:8336
	ds_write_b16 v134, v71 offset:8480
	ds_write_b16_d16_hi v134, v71 offset:8624
	ds_write_b16 v134, v72 offset:8768
	ds_write_b16_d16_hi v134, v72 offset:8912
	ds_write_b16 v134, v73 offset:9056
	ds_write_b16_d16_hi v134, v73 offset:9200

; #define LAS __attribute__((address_space(3)))
; #define PVS(s, pk) do { const bf16x8 a0_ = *(const LAS bf16x8*)(vb + (s) * 32), a1_ = *(const LAS bf16x8*)(vb + 32 * VT_STRIDE + (s) * 32); \
;             o0 = __builtin_amdgcn_mfma_f32_32x32x16_bf16(a0_, pk, o0, 0, 0, 0); o1 = __builtin_amdgcn_mfma_f32_32x32x16_bf16(a1_, pk, o1, 0, 0, 0); } while (0)
; #define PVS(s, pk) do { const bf16x8 a0_ = *(const LAS bf16x8*)(vb + (s) * 32), a1_ = *(const LAS bf16x8*)(vb + 32 * VT_STRIDE + (s) * 32); \
;             o0 = __builtin_amdgcn_mfma_f32_32x32x16_bf16(a0_, pk, o0, 0, 0, 0); o1 = __builtin_amdgcn_mfma_f32_32x32x16_bf16(a1_, pk, o1, 0, 0, 0); } while (0)
; #define PVS(s, pk) do { const bf16x8 a0_ = *(const LAS bf16x8*)(vb + (s) * 32), a1_ = *(const LAS bf16x8*)(vb + 32 * VT_STRIDE + (s) * 32); \
;             o0 = __builtin_amdgcn_mfma_f32_32x32x16_bf16(a0_, pk, o0, 0, 0, 0); o1 = __builtin_amdgcn_mfma_f32_32x32x16_bf16(a1_, pk, o1, 0, 0, 0); } while (0)
; #define PVS(s, pk) do { const bf16x8 a0_ = *(const LAS bf16x8*)(vb + (s) * 32), a1_ = *(const LAS bf16x8*)(vb + 32 * VT_STRIDE + (s) * 32); \
;             o0 = __builtin_amdgcn_mfma_f32_32x32x16_bf16(a0_, pk, o0, 0, 0, 0); o1 = __builtin_amdgcn_mfma_f32_32x32x16_bf16(a1_, pk, o1, 0, 0, 0); } while (0)
; #define PVS(s, pk) do { const bf16x8 a0_ = *(const LAS bf16x8*)(vb + (s) * 32), a1_ = *(const LAS bf16x8*)(vb + 32 * VT_STRIDE + (s) * 32); \
;             o0 = __builtin_amdgcn_mfma_f32_32x32x16_bf16(a0_, pk, o0, 0, 0, 0); o1 = __builtin_amdgcn_mfma_f32_32x32x16_bf16(a1_, pk, o1, 0, 0, 0); } while (0)
; #define PVS(s, pk) do { const bf16x8 a0_ = *(const LAS bf16x8*)(vb + (s) * 32), a1_ = *(const LAS bf16x8*)(vb + 32 * VT_STRIDE + (s) * 32); \
;             o0 = __builtin_amdgcn_mfma_f32_32x32x16_bf16(a0_, pk, o0, 0, 0, 0); o1 = __builtin_amdgcn_mfma_f32_32x32x16_bf16(a1_, pk, o1, 0, 0, 0); } while (0)
; template <int MODE>
; __device__ __forceinline__ void attn_unit(LAS unsigned char* lds, const AttnArgs& A, int qb) {
;     ...
;     if (prev_active) {
;         const LAS unsigned char* vb = lds + prevbuf + KB_BYTES + r32 * VT_STRIDE + hi * 16;
;     ...
;         PVS(0, pkP0); PVS(1, pkP1); PVS(2, pkP2); PVS(3, pkP3);
;     ...
;     }
.LBB0_1220:
	s_waitcnt vmcnt(0)
	s_andn2_b64 vcc, exec, s[12:13]
	s_cbranch_vccnz .LBB0_1155
	s_add_i32 s0, s16, 0
	v_add3_u32 v6, s0, v132, v122
	ds_read_b128 v[2:5], v6 offset:8192
	s_waitcnt lgkmcnt(0)
	v_mfma_f32_32x32x16_bf16 v[50:65], v[2:5], v[118:121], v[50:65]
	ds_read_b128 v[2:5], v6 offset:12800
	s_waitcnt lgkmcnt(0)
	v_mfma_f32_32x32x16_bf16 v[34:49], v[2:5], v[118:121], v[34:49]
	ds_read_b128 v[2:5], v6 offset:8224
	s_waitcnt lgkmcnt(0)
	v_mfma_f32_32x32x16_bf16 v[50:65], v[2:5], v[110:113], v[50:65]
	ds_read_b128 v[2:5], v6 offset:12832
	s_waitcnt lgkmcnt(0)
	v_mfma_f32_32x32x16_bf16 v[34:49], v[2:5], v[110:113], v[34:49]
	ds_read_b128 v[2:5], v6 offset:8256
	s_waitcnt lgkmcnt(0)
	v_mfma_f32_32x32x16_bf16 v[50:65], v[2:5], v[114:117], v[50:65]
	ds_read_b128 v[2:5], v6 offset:12864
	s_waitcnt lgkmcnt(0)
	v_mfma_f32_32x32x16_bf16 v[34:49], v[2:5], v[114:117], v[34:49]
	ds_read_b128 v[2:5], v6 offset:8288
	s_waitcnt lgkmcnt(0)
	v_mfma_f32_32x32x16_bf16 v[50:65], v[2:5], v[106:109], v[50:65]
	ds_read_b128 v[2:5], v6 offset:12896
	s_waitcnt lgkmcnt(0)
	v_mfma_f32_32x32x16_bf16 v[34:49], v[2:5], v[106:109], v[34:49]
	s_branch .LBB0_1155
